# v16 + gm_spatial gating epilogue de-serialised (U/Z loads of 8 elements batched, registers renamed)
# baseline (speedup 1.0000x reference)
.LBB0_1654:
	s_and_b32 s0, s8, 7
	s_mulk_i32 s0, 0x108
	s_ashr_i32 s6, s8, 3
	s_add_i32 s1, s0, s6
	s_bfe_u32 s9, s1, 0x30001
	s_lshl_b32 s6, s6, 7
	s_and_b32 s10, s6, 0x80
	s_lshl_b32 s6, s9, 15
	v_lshl_add_u64 v[0:1], v[60:61], 0, s[6:7]
	v_readfirstlane_b32 s6, v84
	v_add_u32_e32 v6, 0x1000, v84
	s_ashr_i32 s0, s1, 4
	s_mov_b32 m0, s6
	v_readfirstlane_b32 s6, v6
	v_add_u32_e32 v6, 0x2000, v84
	s_ashr_i32 s1, s0, 31
	global_load_lds_dwordx4 v[0:1], off
	v_lshl_add_u64 v[4:5], v[0:1], 0, s[20:21]
	s_mov_b32 m0, s6
	v_readfirstlane_b32 s6, v6
	v_add_u32_e32 v6, 0x3000, v84
	s_lshl_b64 s[12:13], s[0:1], 11
	s_lshl_b32 s1, s9, 8
	global_load_lds_dwordx4 v[4:5], off
	v_lshl_add_u64 v[4:5], v[0:1], 0, s[24:25]
	s_mov_b32 m0, s6
	v_readfirstlane_b32 s6, v6
	s_or_b32 s11, s12, s1
	global_load_lds_dwordx4 v[4:5], off
	v_lshl_add_u64 v[4:5], v[0:1], 0, s[36:37]
	s_mov_b32 m0, s6
	s_or_b32 s12, s11, s10
	global_load_lds_dwordx4 v[4:5], off
	v_add_u32_e32 v4, 0x8000, v84
	s_lshl_b64 s[12:13], s[12:13], 8
	v_readfirstlane_b32 s6, v4
	v_add_u32_e32 v6, 0x9000, v84
	v_lshl_add_u64 v[2:3], v[62:63], 0, s[12:13]
	s_mov_b32 m0, s6
	v_readfirstlane_b32 s6, v6
	v_add_u32_e32 v6, 0xa000, v84
	global_load_lds_dwordx4 v[2:3], off
	v_lshl_add_u64 v[4:5], v[2:3], 0, s[20:21]
	s_mov_b32 m0, s6
	v_readfirstlane_b32 s6, v6
	v_add_u32_e32 v6, 0xb000, v84
	global_load_lds_dwordx4 v[4:5], off
	v_lshl_add_u64 v[4:5], v[2:3], 0, s[24:25]
	s_mov_b32 m0, s6
	v_readfirstlane_b32 s6, v6
	v_add_u32_e32 v16, 0x4000, v84
	global_load_lds_dwordx4 v[4:5], off
	v_lshl_add_u64 v[4:5], v[2:3], 0, s[36:37]
	s_mov_b32 m0, s6
	v_readfirstlane_b32 s6, v16
	global_load_lds_dwordx4 v[4:5], off
	v_lshl_add_u64 v[10:11], v[0:1], 0, s[38:39]
	v_lshl_add_u64 v[12:13], v[0:1], 0, s[40:41]
	v_lshl_add_u64 v[14:15], v[0:1], 0, s[42:43]
	v_lshl_add_u64 v[0:1], v[0:1], 0, s[92:93]
	s_mov_b32 m0, s6
	s_waitcnt vmcnt(0)
	s_waitcnt vmcnt(0) lgkmcnt(0)
	s_barrier
	global_load_lds_dwordx4 v[0:1], off
	v_add_u32_e32 v0, 0x5000, v84
	v_lshl_add_u64 v[4:5], v[2:3], 0, s[38:39]
	v_readfirstlane_b32 s6, v0
	v_add_u32_e32 v0, 0x6000, v84
	s_mov_b32 m0, s6
	v_readfirstlane_b32 s6, v0
	v_add_u32_e32 v0, 0x7000, v84
	global_load_lds_dwordx4 v[14:15], off
	s_mov_b32 m0, s6
	v_readfirstlane_b32 s6, v0
	v_add_u32_e32 v0, 0xc000, v84
	global_load_lds_dwordx4 v[12:13], off
	s_mov_b32 m0, s6
	v_readfirstlane_b32 s6, v0
	v_add_u32_e32 v0, 0xd000, v84
	v_lshl_add_u64 v[6:7], v[2:3], 0, s[40:41]
	v_lshl_add_u64 v[8:9], v[2:3], 0, s[42:43]
	v_lshl_add_u64 v[2:3], v[2:3], 0, s[92:93]
	global_load_lds_dwordx4 v[10:11], off
	s_mov_b32 m0, s6
	v_readfirstlane_b32 s6, v0
	v_add_u32_e32 v0, 0xe000, v84
	global_load_lds_dwordx4 v[2:3], off
	s_mov_b32 m0, s6
	v_readfirstlane_b32 s6, v0
	v_add_u32_e32 v0, 0xf000, v84
	global_load_lds_dwordx4 v[8:9], off
	s_mov_b32 m0, s6
	v_readfirstlane_b32 s6, v0
	global_load_lds_dwordx4 v[6:7], off
	s_mov_b32 m0, s6
	s_nop 0
	global_load_lds_dwordx4 v[4:5], off
	ds_read_b128 v[0:3], v79
	ds_read_b128 v[4:7], v79 offset:2048
	ds_read_b128 v[8:11], v79 offset:4096
	ds_read_b128 v[12:15], v79 offset:6144
	ds_read_b128 v[16:19], v78 offset:32768
	ds_read_b128 v[20:23], v78 offset:34816
	ds_read_b128 v[24:27], v78 offset:36864
	ds_read_b128 v[28:31], v78 offset:38912
	s_setprio 1
	s_waitcnt lgkmcnt(0)
	v_mfma_f32_16x16x32_bf16 v[32:35], v[16:19], v[0:3], 0
	v_mfma_f32_16x16x32_bf16 v[36:39], v[20:23], v[0:3], 0
	v_mfma_f32_16x16x32_bf16 v[40:43], v[24:27], v[0:3], 0
	v_mfma_f32_16x16x32_bf16 v[0:3], v[28:31], v[0:3], 0
	v_mfma_f32_16x16x32_bf16 v[44:47], v[16:19], v[4:7], 0
	v_mfma_f32_16x16x32_bf16 v[48:51], v[20:23], v[4:7], 0
	v_mfma_f32_16x16x32_bf16 v[52:55], v[24:27], v[4:7], 0
	v_mfma_f32_16x16x32_bf16 v[4:7], v[28:31], v[4:7], 0
	v_mfma_f32_16x16x32_bf16 v[56:59], v[16:19], v[8:11], 0
	v_mfma_f32_16x16x32_bf16 v[72:75], v[20:23], v[8:11], 0
	v_mfma_f32_16x16x32_bf16 v[86:89], v[24:27], v[8:11], 0
	v_mfma_f32_16x16x32_bf16 v[8:11], v[28:31], v[8:11], 0
	v_mfma_f32_16x16x32_bf16 v[16:19], v[16:19], v[12:15], 0
	v_mfma_f32_16x16x32_bf16 v[20:23], v[20:23], v[12:15], 0
	v_mfma_f32_16x16x32_bf16 v[24:27], v[24:27], v[12:15], 0
	v_mfma_f32_16x16x32_bf16 v[12:15], v[28:31], v[12:15], 0
	s_setprio 0
	ds_read_b128 v[28:31], v80
	ds_read_b128 v[90:93], v80 offset:2048
	ds_read_b128 v[94:97], v80 offset:4096
	ds_read_b128 v[98:101], v80 offset:6144
	ds_read_b128 v[120:123], v81 offset:32768
	ds_read_b128 v[124:127], v81 offset:34816
	ds_read_b128 v[128:131], v81 offset:36864
	ds_read_b128 v[132:135], v81 offset:38912
	s_setprio 1
	s_waitcnt lgkmcnt(0)
	v_mfma_f32_16x16x32_bf16 v[32:35], v[120:123], v[28:31], v[32:35]
	v_mfma_f32_16x16x32_bf16 v[36:39], v[124:127], v[28:31], v[36:39]
	v_mfma_f32_16x16x32_bf16 v[40:43], v[128:131], v[28:31], v[40:43]
	v_mfma_f32_16x16x32_bf16 v[0:3], v[132:135], v[28:31], v[0:3]
	v_mfma_f32_16x16x32_bf16 v[28:31], v[120:123], v[90:93], v[44:47]
	v_mfma_f32_16x16x32_bf16 v[44:47], v[124:127], v[90:93], v[48:51]
	v_mfma_f32_16x16x32_bf16 v[48:51], v[128:131], v[90:93], v[52:55]
	v_mfma_f32_16x16x32_bf16 v[4:7], v[132:135], v[90:93], v[4:7]
	v_mfma_f32_16x16x32_bf16 v[52:55], v[120:123], v[94:97], v[56:59]
	v_mfma_f32_16x16x32_bf16 v[56:59], v[124:127], v[94:97], v[72:75]
	v_mfma_f32_16x16x32_bf16 v[72:75], v[128:131], v[94:97], v[86:89]
	v_mfma_f32_16x16x32_bf16 v[8:11], v[132:135], v[94:97], v[8:11]
	v_mfma_f32_16x16x32_bf16 v[16:19], v[120:123], v[98:101], v[16:19]
	v_mfma_f32_16x16x32_bf16 v[20:23], v[124:127], v[98:101], v[20:23]
	v_mfma_f32_16x16x32_bf16 v[24:27], v[128:131], v[98:101], v[24:27]
	v_mfma_f32_16x16x32_bf16 v[12:15], v[132:135], v[98:101], v[12:15]
	s_setprio 0
	s_waitcnt vmcnt(0)
	s_waitcnt vmcnt(0)
	s_barrier
	ds_read_b128 v[86:89], v78 offset:55296
	ds_read_b128 v[90:93], v78 offset:53248
	ds_read_b128 v[94:97], v78 offset:51200
	ds_read_b128 v[98:101], v78 offset:49152
	ds_read_b128 v[120:123], v79 offset:22528
	ds_read_b128 v[124:127], v79 offset:20480
	ds_read_b128 v[128:131], v79 offset:18432
	ds_read_b128 v[132:135], v79 offset:16384
	s_setprio 1
	s_waitcnt lgkmcnt(0)
	v_mfma_f32_16x16x32_bf16 v[32:35], v[98:101], v[132:135], v[32:35]
	v_mfma_f32_16x16x32_bf16 v[36:39], v[94:97], v[132:135], v[36:39]
	v_mfma_f32_16x16x32_bf16 v[40:43], v[90:93], v[132:135], v[40:43]
	v_mfma_f32_16x16x32_bf16 v[0:3], v[86:89], v[132:135], v[0:3]
	v_mfma_f32_16x16x32_bf16 v[28:31], v[98:101], v[128:131], v[28:31]
	v_mfma_f32_16x16x32_bf16 v[132:135], v[94:97], v[128:131], v[44:47]
	v_mfma_f32_16x16x32_bf16 v[136:139], v[90:93], v[128:131], v[48:51]
	v_mfma_f32_16x16x32_bf16 v[4:7], v[86:89], v[128:131], v[4:7]
	v_mfma_f32_16x16x32_bf16 v[128:131], v[98:101], v[124:127], v[52:55]
	v_mfma_f32_16x16x32_bf16 v[140:143], v[94:97], v[124:127], v[56:59]
	v_mfma_f32_16x16x32_bf16 v[72:75], v[90:93], v[124:127], v[72:75]
	v_mfma_f32_16x16x32_bf16 v[8:11], v[86:89], v[124:127], v[8:11]
	v_mfma_f32_16x16x32_bf16 v[98:101], v[98:101], v[120:123], v[16:19]
	v_mfma_f32_16x16x32_bf16 v[94:97], v[94:97], v[120:123], v[20:23]
	v_mfma_f32_16x16x32_bf16 v[90:93], v[90:93], v[120:123], v[24:27]
	v_mfma_f32_16x16x32_bf16 v[86:89], v[86:89], v[120:123], v[12:15]
	s_setprio 0
	s_nop 1
	ds_read_b128 v[12:15], v80 offset:16384
	ds_read_b128 v[16:19], v80 offset:18432
	ds_read_b128 v[120:123], v80 offset:20480
	ds_read_b128 v[124:127], v80 offset:22528
	ds_read_b128 v[144:147], v81 offset:49152
	ds_read_b128 v[148:151], v81 offset:51200
	ds_read_b128 v[152:155], v81 offset:53248
	ds_read_b128 v[156:159], v81 offset:55296
	s_setprio 1
	s_waitcnt lgkmcnt(3)
	v_mfma_f32_16x16x32_bf16 v[160:163], v[144:147], v[12:15], v[32:35]
	s_waitcnt lgkmcnt(2)
	v_mfma_f32_16x16x32_bf16 v[56:59], v[148:151], v[12:15], v[36:39]
	s_waitcnt lgkmcnt(1)
	v_mfma_f32_16x16x32_bf16 v[52:55], v[152:155], v[12:15], v[40:43]
	s_waitcnt lgkmcnt(0)
	v_mfma_f32_16x16x32_bf16 v[48:51], v[156:159], v[12:15], v[0:3]
	v_mfma_f32_16x16x32_bf16 v[44:47], v[144:147], v[16:19], v[28:31]
	v_mfma_f32_16x16x32_bf16 v[40:43], v[148:151], v[16:19], v[132:135]
	v_mfma_f32_16x16x32_bf16 v[36:39], v[152:155], v[16:19], v[136:139]
	v_mfma_f32_16x16x32_bf16 v[32:35], v[156:159], v[16:19], v[4:7]
	v_mfma_f32_16x16x32_bf16 v[28:31], v[144:147], v[120:123], v[128:131]
	v_mfma_f32_16x16x32_bf16 v[24:27], v[148:151], v[120:123], v[140:143]
	v_mfma_f32_16x16x32_bf16 v[20:23], v[152:155], v[120:123], v[72:75]
	v_mfma_f32_16x16x32_bf16 v[16:19], v[156:159], v[120:123], v[8:11]
	v_mfma_f32_16x16x32_bf16 v[12:15], v[144:147], v[124:127], v[98:101]
	v_mfma_f32_16x16x32_bf16 v[8:11], v[148:151], v[124:127], v[94:97]
	v_mfma_f32_16x16x32_bf16 v[4:7], v[152:155], v[124:127], v[90:93]
	v_mfma_f32_16x16x32_bf16 v[0:3], v[156:159], v[124:127], v[86:89]
	s_setprio 0
	s_lshl_b32 s0, s0, 7
	v_mov_b32_e32 v91, v75
	v_add_u32_e32 v90, s0, v71
	v_or_b32_e32 v85, s10, v76
	v_mov_b32_e32 v92, v90
	v_ashrrev_i32_e32 v93, 31, v90
	v_or_b32_e32 v90, s1, v85
	v_lshlrev_b64 v[94:95], 11, v[92:93]
	v_mov_b32_e32 v93, v73
	v_lshl_add_u32 v92, s9, 7, v71
	v_mov_b32_e32 v97, v89
	v_or_b32_e32 v96, v94, v90
	v_mov_b32_e32 v98, v96
	v_mov_b32_e32 v99, v95
	v_mov_b32_e32 v96, v92
	v_ashrrev_i32_e32 v97, 31, v92
	v_lshlrev_b64 v[92:93], 1, v[98:99]
	v_lshl_add_u64 v[98:99], v[96:97], 2, s[68:69]
	v_lshl_add_u64 v[96:97], s[90:91], 0, v[92:93]
	v_lshl_add_u64 v[100:101], s[86:87], 0, v[92:93]
	s_barrier
	v_mov_b32_e32 v93, v69
	global_load_dword v92, v[98:99], off
	global_load_dwordx2 v[102:103], v[96:97], off
	global_load_dwordx2 v[120:121], v[100:101], off
	s_add_i32 s8, s8, s84
	s_cmpk_lt_i32 s8, 0x840
	v_mov_b32_e32 v100, v94
	v_mov_b32_e32 v122, v100
	v_mov_b32_e32 v125, v97
	v_mov_b32_e32 v127, v99
	v_or_b32_e32 v85, 16, v90
	v_or_b32_e32 v128, v94, v85
	v_mov_b32_e32 v130, v128
	v_mov_b32_e32 v131, v95
	v_lshlrev_b64 v[132:133], 1, v[130:131]
	v_lshl_add_u64 v[130:131], s[90:91], 0, v[132:133]
	v_lshl_add_u64 v[134:135], s[86:87], 0, v[132:133]
	global_load_dwordx2 v[132:133], v[130:131], off
	global_load_dwordx2 v[144:145], v[134:135], off
	v_or_b32_e32 v91, 32, v90
	v_or_b32_e32 v134, v94, v91
	v_mov_b32_e32 v146, v134
	v_mov_b32_e32 v147, v95
	v_lshlrev_b64 v[148:149], 1, v[146:147]
	v_lshl_add_u64 v[146:147], s[90:91], 0, v[148:149]
	v_lshl_add_u64 v[150:151], s[86:87], 0, v[148:149]
	global_load_dwordx2 v[148:149], v[146:147], off
	global_load_dwordx2 v[152:153], v[150:151], off
	v_or_b32_e32 v150, 48, v90
	v_mov_b32_e32 v155, v95
	v_or_b32_e32 v154, v94, v150
	v_lshlrev_b64 v[94:95], 1, v[154:155]
	v_lshl_add_u64 v[154:155], s[90:91], 0, v[94:95]
	v_lshl_add_u64 v[156:157], s[86:87], 0, v[94:95]
	global_load_dwordx2 v[94:95], v[154:155], off
	global_load_dwordx2 v[158:159], v[156:157], off
	v_mov_b32_e32 v156, v146
	v_add_u32_e32 v164, s0, v82
	v_mov_b32_e32 v166, v164
	v_ashrrev_i32_e32 v167, 31, v164
	v_lshlrev_b64 v[168:169], 11, v[166:167]
	v_or_b32_e32 v166, v168, v90
	v_mov_b32_e32 v170, v166
	v_mov_b32_e32 v171, v169
	v_lshlrev_b64 v[172:173], 1, v[170:171]
	v_lshl_add_u64 v[170:171], s[90:91], 0, v[172:173]
	v_lshl_add_u64 v[174:175], s[86:87], 0, v[172:173]
	global_load_dword v172, v[98:99], off offset:64
	global_load_dwordx2 v[176:177], v[170:171], off
	global_load_dwordx2 v[178:179], v[174:175], off
	v_or_b32_e32 v174, v168, v85
	v_mov_b32_e32 v184, v174
	v_mov_b32_e32 v185, v169
	v_lshlrev_b64 v[186:187], 1, v[184:185]
	v_lshl_add_u64 v[184:185], s[90:91], 0, v[186:187]
	v_lshl_add_u64 v[188:189], s[86:87], 0, v[186:187]
	global_load_dwordx2 v[186:187], v[184:185], off
	global_load_dwordx2 v[190:191], v[188:189], off
	v_mov_b32_e32 v188, v170
	v_or_b32_e32 v192, v168, v91
	v_mov_b32_e32 v194, v192
	v_mov_b32_e32 v195, v169
	v_lshlrev_b64 v[196:197], 1, v[194:195]
	v_lshl_add_u64 v[194:195], s[90:91], 0, v[196:197]
	v_lshl_add_u64 v[198:199], s[86:87], 0, v[196:197]
	global_load_dwordx2 v[196:197], v[194:195], off
	global_load_dwordx2 v[200:201], v[198:199], off
	v_mov_b32_e32 v199, v169
	v_or_b32_e32 v198, v168, v150
	v_mov_b32_e32 v168, v184
	v_lshlrev_b64 v[202:203], 1, v[198:199]
	v_lshl_add_u64 v[204:205], s[90:91], 0, v[202:203]
	v_lshl_add_u64 v[206:207], s[86:87], 0, v[202:203]
	global_load_dwordx2 v[202:203], v[204:205], off
	global_load_dwordx2 v[208:209], v[206:207], off
	v_mov_b32_e32 v206, v198
	v_mov_b32_e32 v198, v194
	v_add_u32_e32 v210, s0, v83
	v_mov_b32_e32 v212, v210
	v_ashrrev_i32_e32 v213, 31, v210
	v_lshlrev_b64 v[214:215], 11, v[212:213]
	v_or_b32_e32 v212, v214, v90
	v_mov_b32_e32 v216, v212
	v_mov_b32_e32 v217, v215
	v_lshlrev_b64 v[218:219], 1, v[216:217]
	s_waitcnt vmcnt(0)
	v_pk_add_f32 v[216:217], v[162:163], v[92:93] op_sel_hi:[1,0]
	v_and_b32_e32 v101, 0xffff0000, v121
	s_nop 0
	v_mov_b32_e32 v221, v101
	v_lshlrev_b32_e32 v220, 16, v121
	v_mov_b32_e32 v100, v120
	v_and_b32_e32 v101, 0xffff0000, v120
	s_nop 0
	v_mov_b32_e32 v121, v101
	v_lshlrev_b32_e32 v120, 16, v100
	s_nop 0
	v_mul_f32_e32 v100, 0xbfb8aa3b, v120
	s_nop 0
	v_exp_f32_e32 v101, v100
	v_and_b32_e32 v123, 0xffff0000, v103
	s_nop 0
	v_mov_b32_e32 v223, v123
	v_lshlrev_b32_e32 v222, 16, v103
	v_mov_b32_e32 v122, v102
	v_and_b32_e32 v123, 0xffff0000, v102
	v_add_f32_e32 v100, 1.0, v101
	s_nop 0
	v_rcp_f32_e32 v124, v100
	v_mul_f32_e32 v100, 0xbfb8aa3b, v121
	s_nop 0
	v_exp_f32_e32 v101, v100
	v_mov_b32_e32 v103, v123
	v_lshlrev_b32_e32 v102, 16, v122
	v_pk_add_f32 v[122:123], v[160:161], v[92:93] op_sel_hi:[1,0]
	v_pk_mul_f32 v[224:225], v[216:217], v[222:223]
	v_add_f32_e32 v100, 1.0, v101
	v_mov_b32_e32 v216, v124
	v_rcp_f32_e32 v217, v100
	v_mul_f32_e32 v100, 0xbfb8aa3b, v220
	s_nop 0
	v_exp_f32_e32 v101, v100
	v_pk_mul_f32 v[124:125], v[122:123], v[102:103]
	v_pk_mul_f32 v[102:103], v[216:217], v[120:121]
	v_pk_add_f32 v[120:121], v[58:59], v[92:93] op_sel_hi:[1,0]
	v_add_f32_e32 v100, 1.0, v101
	s_nop 0
	v_rcp_f32_e32 v126, v100
	v_mul_f32_e32 v100, 0xbfb8aa3b, v221
	s_nop 0
	v_exp_f32_e32 v101, v100
	v_pk_mul_f32 v[122:123], v[124:125], v[102:103]
	v_pk_add_f32 v[102:103], v[56:57], v[92:93] op_sel_hi:[1,0]
	v_mov_b32_e32 v125, v123
	v_cvt_pk_bf16_f32 v124, v122, v123
	v_add_f32_e32 v100, 1.0, v101
	v_mov_b32_e32 v122, v126
	v_rcp_f32_e32 v123, v100
	v_pk_add_f32 v[100:101], v[54:55], v[92:93] op_sel_hi:[1,0]
	v_pk_add_f32 v[126:127], v[52:53], v[92:93] op_sel_hi:[1,0]
	v_pk_mul_f32 v[222:223], v[122:123], v[220:221]
	v_pk_add_f32 v[220:221], v[50:51], v[92:93] op_sel_hi:[1,0]
	v_pk_mul_f32 v[226:227], v[224:225], v[222:223]
	v_pk_add_f32 v[222:223], v[48:49], v[92:93] op_sel_hi:[1,0]
	v_mov_b32_e32 v92, v124
	v_cvt_pk_bf16_f32 v93, v226, v227
	global_store_dwordx2 v[96:97], v[92:93], off
	v_mov_b32_e32 v129, v93
	v_mov_b32_e32 v92, v224
	v_and_b32_e32 v93, 0xffff0000, v133
	v_mov_b32_e32 v96, v226
	v_and_b32_e32 v97, 0xffff0000, v145
	s_nop 0
	v_mov_b32_e32 v125, v97
	v_lshlrev_b32_e32 v124, 16, v145
	v_mov_b32_e32 v96, v144
	v_and_b32_e32 v97, 0xffff0000, v144
	s_nop 0
	v_mov_b32_e32 v129, v97
	v_lshlrev_b32_e32 v128, 16, v96
	s_nop 0
	v_mul_f32_e32 v96, 0xbfb8aa3b, v128
	s_nop 0
	v_exp_f32_e32 v97, v96
	v_mov_b32_e32 v145, v93
	v_lshlrev_b32_e32 v144, 16, v133
	v_mov_b32_e32 v92, v132
	v_and_b32_e32 v93, 0xffff0000, v132
	s_nop 0
	v_mov_b32_e32 v133, v93
	v_lshlrev_b32_e32 v132, 16, v92
	v_add_f32_e32 v92, 1.0, v97
	v_mov_b32_e32 v97, v217
	v_rcp_f32_e32 v96, v92
	v_mul_f32_e32 v92, 0xbfb8aa3b, v129
	s_nop 0
	v_exp_f32_e32 v93, v92
	v_pk_mul_f32 v[216:217], v[102:103], v[132:133]
	v_pk_mul_f32 v[102:103], v[120:121], v[144:145]
	v_add_f32_e32 v92, 1.0, v93
	v_mov_b32_e32 v120, v96
	v_rcp_f32_e32 v121, v92
	v_mul_f32_e32 v92, 0xbfb8aa3b, v124
	s_nop 0
	v_exp_f32_e32 v93, v92
	v_pk_mul_f32 v[96:97], v[120:121], v[128:129]
	s_nop 0
	v_pk_mul_f32 v[128:129], v[216:217], v[96:97]
	v_add_f32_e32 v92, 1.0, v93
	v_mov_b32_e32 v97, v123
	v_rcp_f32_e32 v96, v92
	v_mul_f32_e32 v92, 0xbfb8aa3b, v125
	s_nop 0
	v_exp_f32_e32 v93, v92
	v_mov_b32_e32 v123, v129
	v_cvt_pk_bf16_f32 v122, v128, v129
	v_add_f32_e32 v92, 1.0, v93
	v_mov_b32_e32 v128, v96
	v_rcp_f32_e32 v129, v92
	s_nop 0
	v_pk_mul_f32 v[92:93], v[128:129], v[124:125]
	s_nop 0
	v_pk_mul_f32 v[96:97], v[102:103], v[92:93]
	v_mov_b32_e32 v102, v122
	v_cvt_pk_bf16_f32 v103, v96, v97
	global_store_dwordx2 v[130:131], v[102:103], off
	v_mov_b32_e32 v135, v97
	v_mov_b32_e32 v96, v128
	v_and_b32_e32 v97, 0xffff0000, v149
	v_mov_b32_e32 v102, v92
	v_and_b32_e32 v103, 0xffff0000, v153
	s_nop 0
	v_mov_b32_e32 v93, v103
	v_lshlrev_b32_e32 v92, 16, v153
	v_mov_b32_e32 v102, v152
	v_and_b32_e32 v103, 0xffff0000, v152
	s_nop 0
	v_mov_b32_e32 v123, v103
	v_lshlrev_b32_e32 v122, 16, v102
	s_nop 0
	v_mul_f32_e32 v102, 0xbfb8aa3b, v122
	s_nop 0
	v_exp_f32_e32 v103, v102
	v_mov_b32_e32 v129, v97
	v_lshlrev_b32_e32 v128, 16, v149
	v_mov_b32_e32 v96, v148
	v_and_b32_e32 v97, 0xffff0000, v148
	s_nop 0
	v_mov_b32_e32 v131, v97
	v_lshlrev_b32_e32 v130, 16, v96
	v_add_f32_e32 v96, 1.0, v103
	v_mov_b32_e32 v103, v125
	v_rcp_f32_e32 v102, v96
	v_mul_f32_e32 v96, 0xbfb8aa3b, v123
	s_nop 0
	v_exp_f32_e32 v97, v96
	v_pk_mul_f32 v[124:125], v[126:127], v[130:131]
	v_pk_mul_f32 v[126:127], v[100:101], v[128:129]
	v_add_f32_e32 v96, 1.0, v97
	v_mov_b32_e32 v100, v102
	v_rcp_f32_e32 v101, v96
	v_mul_f32_e32 v96, 0xbfb8aa3b, v92
	s_nop 0
	v_exp_f32_e32 v97, v96
	v_pk_mul_f32 v[102:103], v[100:101], v[122:123]
	s_nop 0
	v_pk_mul_f32 v[122:123], v[124:125], v[102:103]
	v_add_f32_e32 v96, 1.0, v97
	v_mov_b32_e32 v103, v121
	v_rcp_f32_e32 v102, v96
	v_mul_f32_e32 v96, 0xbfb8aa3b, v93
	s_nop 0
	v_exp_f32_e32 v97, v96
	v_mov_b32_e32 v121, v123
	v_cvt_pk_bf16_f32 v120, v122, v123
	v_add_f32_e32 v96, 1.0, v97
	v_mov_b32_e32 v122, v102
	v_rcp_f32_e32 v123, v96
	s_nop 0
	v_pk_mul_f32 v[96:97], v[122:123], v[92:93]
	s_nop 0
	v_pk_mul_f32 v[102:103], v[126:127], v[96:97]
	v_mov_b32_e32 v122, v120
	v_cvt_pk_bf16_f32 v123, v102, v103
	global_store_dwordx2 v[146:147], v[122:123], off
	v_mov_b32_e32 v102, v100
	v_and_b32_e32 v103, 0xffff0000, v95
	v_and_b32_e32 v157, 0xffff0000, v159
	s_nop 0
	v_mov_b32_e32 v101, v157
	v_lshlrev_b32_e32 v100, 16, v159
	v_mov_b32_e32 v120, v158
	v_and_b32_e32 v121, 0xffff0000, v158
	s_nop 0
	v_mov_b32_e32 v123, v121
	v_lshlrev_b32_e32 v122, 16, v120
	s_nop 0
	v_mul_f32_e32 v120, 0xbfb8aa3b, v122
	s_nop 0
	v_exp_f32_e32 v121, v120
	v_mov_b32_e32 v125, v103
	v_lshlrev_b32_e32 v124, 16, v95
	v_mov_b32_e32 v102, v94
	v_and_b32_e32 v103, 0xffff0000, v94
	s_nop 0
	v_mov_b32_e32 v95, v103
	v_lshlrev_b32_e32 v94, 16, v102
	v_add_f32_e32 v102, 1.0, v121
	v_mov_b32_e32 v121, v97
	v_rcp_f32_e32 v120, v102
	v_mul_f32_e32 v96, 0xbfb8aa3b, v123
	s_nop 0
	v_exp_f32_e32 v97, v96
	v_pk_mul_f32 v[102:103], v[222:223], v[94:95]
	v_pk_mul_f32 v[94:95], v[220:221], v[124:125]
	v_add_f32_e32 v96, 1.0, v97
	v_mov_b32_e32 v126, v120
	v_rcp_f32_e32 v127, v96
	v_mul_f32_e32 v96, 0xbfb8aa3b, v100
	s_nop 0
	v_exp_f32_e32 v97, v96
	v_pk_mul_f32 v[120:121], v[126:127], v[122:123]
	s_nop 0
	v_pk_mul_f32 v[122:123], v[102:103], v[120:121]
	v_add_f32_e32 v96, 1.0, v97
	v_mov_b32_e32 v103, v93
	v_rcp_f32_e32 v102, v96
	v_mul_f32_e32 v92, 0xbfb8aa3b, v101
	s_nop 0
	v_exp_f32_e32 v93, v92
	v_mov_b32_e32 v97, v123
	v_cvt_pk_bf16_f32 v96, v122, v123
	v_add_f32_e32 v92, 1.0, v93
	v_mov_b32_e32 v122, v102
	v_rcp_f32_e32 v123, v92
	s_nop 0
	v_pk_mul_f32 v[92:93], v[122:123], v[100:101]
	s_nop 0
	v_pk_mul_f32 v[102:103], v[94:95], v[92:93]
	v_mov_b32_e32 v92, v96
	v_cvt_pk_bf16_f32 v93, v102, v103
	v_mov_b32_e32 v165, v103
	v_mov_b32_e32 v167, v121
	global_store_dwordx2 v[154:155], v[92:93], off
	v_mov_b32_e32 v173, v93
	v_mov_b32_e32 v92, v124
	v_and_b32_e32 v93, 0xffff0000, v177
	v_mov_b32_e32 v94, v100
	v_and_b32_e32 v95, 0xffff0000, v179
	s_nop 0
	v_mov_b32_e32 v97, v95
	v_lshlrev_b32_e32 v96, 16, v179
	v_mov_b32_e32 v94, v178
	v_and_b32_e32 v95, 0xffff0000, v178
	s_nop 0
	v_mov_b32_e32 v101, v95
	v_lshlrev_b32_e32 v100, 16, v94
	s_nop 0
	v_mul_f32_e32 v94, 0xbfb8aa3b, v100
	s_nop 0
	v_exp_f32_e32 v95, v94
	v_mov_b32_e32 v103, v93
	v_lshlrev_b32_e32 v102, 16, v177
	v_mov_b32_e32 v92, v176
	v_and_b32_e32 v93, 0xffff0000, v176
	s_nop 0
	v_mov_b32_e32 v121, v93
	v_lshlrev_b32_e32 v120, 16, v92
	v_add_f32_e32 v92, 1.0, v95
	v_mov_b32_e32 v95, v127
	v_rcp_f32_e32 v94, v92
	v_mul_f32_e32 v92, 0xbfb8aa3b, v101
	s_nop 0
	v_exp_f32_e32 v93, v92
	s_nop 0
	v_add_f32_e32 v92, 1.0, v93
	v_mov_b32_e32 v124, v94
	v_rcp_f32_e32 v125, v92
	v_mul_f32_e32 v92, 0xbfb8aa3b, v96
	s_nop 0
	v_exp_f32_e32 v93, v92
	v_pk_mul_f32 v[94:95], v[124:125], v[100:101]
	v_mov_b32_e32 v100, v172
	v_add_f32_e32 v101, 1.0, v93
	v_mov_b32_e32 v93, v123
	v_rcp_f32_e32 v92, v101
	v_pk_add_f32 v[122:123], v[46:47], v[100:101] op_sel_hi:[1,0]
	v_pk_add_f32 v[126:127], v[44:45], v[100:101] op_sel_hi:[1,0]
	v_mul_f32_e32 v128, 0xbfb8aa3b, v97
	s_nop 0
	v_exp_f32_e32 v129, v128
	v_pk_mul_f32 v[130:131], v[126:127], v[120:121]
	v_pk_mul_f32 v[120:121], v[122:123], v[102:103]
	v_pk_mul_f32 v[102:103], v[130:131], v[94:95]
	v_add_f32_e32 v94, 1.0, v129
	v_mov_b32_e32 v122, v92
	v_rcp_f32_e32 v123, v94
	v_mov_b32_e32 v93, v103
	v_cvt_pk_bf16_f32 v92, v102, v103
	v_pk_mul_f32 v[94:95], v[122:123], v[96:97]
	s_nop 0
	v_pk_mul_f32 v[102:103], v[120:121], v[94:95]
	v_mov_b32_e32 v120, v92
	v_cvt_pk_bf16_f32 v121, v102, v103
	global_store_dwordx2 v[170:171], v[120:121], off
	v_mov_b32_e32 v175, v121
	v_mov_b32_e32 v92, v124
	v_and_b32_e32 v93, 0xffff0000, v187
	v_and_b32_e32 v189, 0xffff0000, v191
	s_nop 0
	v_mov_b32_e32 v103, v189
	v_lshlrev_b32_e32 v102, 16, v191
	v_mov_b32_e32 v120, v190
	v_and_b32_e32 v121, 0xffff0000, v190
	s_nop 0
	v_mov_b32_e32 v123, v121
	v_lshlrev_b32_e32 v122, 16, v120
	s_nop 0
	v_mul_f32_e32 v120, 0xbfb8aa3b, v122
	s_nop 0
	v_exp_f32_e32 v121, v120
	v_mov_b32_e32 v125, v93
	v_lshlrev_b32_e32 v124, 16, v187
	v_mov_b32_e32 v92, v186
	v_and_b32_e32 v93, 0xffff0000, v186
	s_nop 0
	v_mov_b32_e32 v127, v93
	v_lshlrev_b32_e32 v126, 16, v92
	v_add_f32_e32 v92, 1.0, v121
	v_mov_b32_e32 v121, v95
	v_rcp_f32_e32 v120, v92
	v_mul_f32_e32 v92, 0xbfb8aa3b, v123
	s_nop 0
	v_exp_f32_e32 v93, v92
	s_nop 0
	v_add_f32_e32 v92, 1.0, v93
	v_mov_b32_e32 v94, v120
	v_rcp_f32_e32 v95, v92
	v_mul_f32_e32 v92, 0xbfb8aa3b, v102
	s_nop 0
	v_exp_f32_e32 v93, v92
	v_pk_mul_f32 v[120:121], v[94:95], v[122:123]
	v_mov_b32_e32 v122, v100
	v_add_f32_e32 v123, 1.0, v93
	v_mov_b32_e32 v93, v97
	v_rcp_f32_e32 v92, v123
	v_pk_add_f32 v[96:97], v[42:43], v[122:123] op_sel_hi:[1,0]
	v_pk_add_f32 v[100:101], v[40:41], v[122:123] op_sel_hi:[1,0]
	v_mul_f32_e32 v128, 0xbfb8aa3b, v103
	s_nop 0
	v_exp_f32_e32 v129, v128
	v_pk_mul_f32 v[130:131], v[100:101], v[126:127]
	v_pk_mul_f32 v[100:101], v[96:97], v[124:125]
	v_pk_mul_f32 v[96:97], v[130:131], v[120:121]
	v_add_f32_e32 v120, 1.0, v129
	v_mov_b32_e32 v124, v92
	v_rcp_f32_e32 v125, v120
	v_mov_b32_e32 v93, v97
	v_cvt_pk_bf16_f32 v92, v96, v97
	v_pk_mul_f32 v[96:97], v[124:125], v[102:103]
	s_nop 0
	v_pk_mul_f32 v[120:121], v[100:101], v[96:97]
	v_mov_b32_e32 v100, v92
	v_cvt_pk_bf16_f32 v101, v120, v121
	global_store_dwordx2 v[184:185], v[100:101], off
	v_mov_b32_e32 v193, v101
	v_mov_b32_e32 v92, v94
	v_and_b32_e32 v93, 0xffff0000, v197
	v_and_b32_e32 v169, 0xffff0000, v201
	s_nop 0
	v_mov_b32_e32 v95, v169
	v_lshlrev_b32_e32 v94, 16, v201
	v_mov_b32_e32 v100, v200
	v_and_b32_e32 v101, 0xffff0000, v200
	s_nop 0
	v_mov_b32_e32 v121, v101
	v_lshlrev_b32_e32 v120, 16, v100
	s_nop 0
	v_mul_f32_e32 v100, 0xbfb8aa3b, v120
	s_nop 0
	v_exp_f32_e32 v101, v100
	v_mov_b32_e32 v125, v93
	v_lshlrev_b32_e32 v124, 16, v197
	v_mov_b32_e32 v92, v196
	v_and_b32_e32 v93, 0xffff0000, v196
	s_nop 0
	v_mov_b32_e32 v127, v93
	v_lshlrev_b32_e32 v126, 16, v92
	v_add_f32_e32 v92, 1.0, v101
	v_mov_b32_e32 v101, v97
	v_rcp_f32_e32 v100, v92
	v_mul_f32_e32 v92, 0xbfb8aa3b, v121
	s_nop 0
	v_exp_f32_e32 v93, v92
	s_nop 0
	v_add_f32_e32 v92, 1.0, v93
	v_mov_b32_e32 v96, v100
	v_rcp_f32_e32 v97, v92
	v_mul_f32_e32 v92, 0xbfb8aa3b, v94
	s_nop 0
	v_exp_f32_e32 v93, v92
	v_pk_mul_f32 v[100:101], v[96:97], v[120:121]
	v_mov_b32_e32 v96, v122
	v_add_f32_e32 v97, 1.0, v93
	s_nop 0
	v_pk_add_f32 v[92:93], v[36:37], v[96:97] op_sel_hi:[1,0]
	v_mov_b32_e32 v121, v103
	v_rcp_f32_e32 v120, v97
	v_pk_mul_f32 v[102:103], v[92:93], v[126:127]
	v_mul_f32_e32 v92, 0xbfb8aa3b, v95
	s_nop 0
	v_exp_f32_e32 v93, v92
	v_pk_add_f32 v[122:123], v[38:39], v[96:97] op_sel_hi:[1,0]
	v_pk_mul_f32 v[126:127], v[102:103], v[100:101]
	v_pk_mul_f32 v[100:101], v[122:123], v[124:125]
	v_add_f32_e32 v92, 1.0, v93
	v_mov_b32_e32 v102, v120
	v_rcp_f32_e32 v103, v92
	v_mov_b32_e32 v93, v127
	v_cvt_pk_bf16_f32 v92, v126, v127
	v_pk_add_f32 v[120:121], v[32:33], v[96:97] op_sel_hi:[1,0]
	v_pk_add_f32 v[122:123], v[34:35], v[96:97] op_sel_hi:[1,0]
	v_pk_mul_f32 v[124:125], v[102:103], v[94:95]
	s_nop 0
	v_pk_mul_f32 v[102:103], v[100:101], v[124:125]
	v_mov_b32_e32 v100, v92
	v_cvt_pk_bf16_f32 v101, v102, v103
	global_store_dwordx2 v[194:195], v[100:101], off
	v_and_b32_e32 v207, 0xffff0000, v203
	v_and_b32_e32 v199, 0xffff0000, v209
	s_nop 0
	v_mov_b32_e32 v93, v199
	v_lshlrev_b32_e32 v92, 16, v209
	v_mov_b32_e32 v100, v208
	v_and_b32_e32 v101, 0xffff0000, v208
	s_nop 0
	v_mov_b32_e32 v103, v101
	v_lshlrev_b32_e32 v102, 16, v100
	v_mov_b32_e32 v101, v207
	v_lshlrev_b32_e32 v100, 16, v203
	v_mov_b32_e32 v124, v202
	v_and_b32_e32 v125, 0xffff0000, v202
	s_nop 0
	v_mov_b32_e32 v127, v125
	v_lshlrev_b32_e32 v126, 16, v124
	v_mul_f32_e32 v124, 0xbfb8aa3b, v102
	v_mul_f32_e32 v125, 0xbfb8aa3b, v103
	v_mul_f32_e32 v128, 0xbfb8aa3b, v92
	v_pk_mul_f32 v[130:131], v[120:121], v[126:127]
	v_mul_f32_e32 v120, 0xbfb8aa3b, v93
	v_exp_f32_e32 v121, v124
	v_exp_f32_e32 v124, v125
	v_exp_f32_e32 v125, v128
	v_exp_f32_e32 v126, v120
	v_add_f32_e32 v120, 1.0, v121
	v_add_f32_e32 v121, 1.0, v124
	v_add_f32_e32 v124, 1.0, v125
	v_add_f32_e32 v125, 1.0, v126
	v_mov_b32_e32 v127, v121
	v_rcp_f32_e32 v126, v120
	s_nop 0
	v_mov_b32_e32 v120, v126
	v_rcp_f32_e32 v121, v127
	v_mov_b32_e32 v127, v95
	v_rcp_f32_e32 v126, v124
	s_nop 0
	v_mov_b32_e32 v94, v126
	v_rcp_f32_e32 v95, v125
	v_pk_mul_f32 v[124:125], v[122:123], v[100:101]
	v_pk_mul_f32 v[100:101], v[120:121], v[102:103]
	v_pk_mul_f32 v[102:103], v[94:95], v[92:93]
	s_nop 0
	v_pk_mul_f32 v[122:123], v[124:125], v[102:103]
	v_pk_mul_f32 v[102:103], v[130:131], v[100:101]
	s_nop 0
	v_mov_b32_e32 v125, v103
	v_cvt_pk_bf16_f32 v124, v102, v103
	s_nop 0
	v_mov_b32_e32 v102, v124
	v_cvt_pk_bf16_f32 v103, v122, v123
	v_mov_b32_e32 v211, v123
	v_mov_b32_e32 v213, v101
	global_store_dwordx2 v[204:205], v[102:103], off
	v_lshl_add_u64 v[100:101], s[90:91], 0, v[218:219]
	v_lshl_add_u64 v[122:123], s[86:87], 0, v[218:219]
	global_load_dword v124, v[98:99], off offset:128
	global_load_dwordx2 v[126:127], v[100:101], off
	global_load_dwordx2 v[128:129], v[122:123], off
	v_or_b32_e32 v122, v214, v85
	v_mov_b32_e32 v130, v122
	v_mov_b32_e32 v131, v215
	v_lshlrev_b64 v[132:133], 1, v[130:131]
	v_lshl_add_u64 v[130:131], s[90:91], 0, v[132:133]
	v_lshl_add_u64 v[134:135], s[86:87], 0, v[132:133]
	global_load_dwordx2 v[132:133], v[130:131], off
	global_load_dwordx2 v[144:145], v[134:135], off
	v_mov_b32_e32 v134, v100
	v_or_b32_e32 v146, v214, v91
	v_mov_b32_e32 v148, v146
	v_mov_b32_e32 v149, v215
	v_lshlrev_b64 v[152:153], 1, v[148:149]
	v_lshl_add_u64 v[148:149], s[90:91], 0, v[152:153]
	v_lshl_add_u64 v[154:155], s[86:87], 0, v[152:153]
	global_load_dwordx2 v[152:153], v[148:149], off
	global_load_dwordx2 v[156:157], v[154:155], off
	v_mov_b32_e32 v155, v215
	v_or_b32_e32 v154, v214, v150
	v_mov_b32_e32 v158, v130
	v_lshlrev_b64 v[164:165], 1, v[154:155]
	v_lshl_add_u64 v[166:167], s[90:91], 0, v[164:165]
	v_lshl_add_u64 v[168:169], s[86:87], 0, v[164:165]
	global_load_dwordx2 v[164:165], v[166:167], off
	global_load_dwordx2 v[170:171], v[168:169], off
	v_mov_b32_e32 v168, v154
	v_mov_b32_e32 v154, v148
	v_add_u32_e32 v172, s0, v77
	v_mov_b32_e32 v174, v172
	v_ashrrev_i32_e32 v175, 31, v172
	v_lshlrev_b64 v[176:177], 11, v[174:175]
	v_or_b32_e32 v174, v176, v90
	v_mov_b32_e32 v178, v174
	v_mov_b32_e32 v179, v177
	v_lshlrev_b64 v[184:185], 1, v[178:179]
	v_lshl_add_u64 v[178:179], s[90:91], 0, v[184:185]
	v_lshl_add_u64 v[186:187], s[86:87], 0, v[184:185]
	global_load_dword v184, v[98:99], off offset:192
	global_load_dwordx2 v[98:99], v[178:179], off
	global_load_dwordx2 v[188:189], v[186:187], off
	v_or_b32_e32 v186, v176, v85
	v_mov_b32_e32 v190, v186
	v_mov_b32_e32 v191, v177
	v_lshlrev_b64 v[192:193], 1, v[190:191]
	v_lshl_add_u64 v[190:191], s[90:91], 0, v[192:193]
	v_lshl_add_u64 v[194:195], s[86:87], 0, v[192:193]
	global_load_dwordx2 v[192:193], v[190:191], off
	global_load_dwordx2 v[196:197], v[194:195], off
	v_mov_b32_e32 v194, v178
	v_or_b32_e32 v198, v176, v91
	v_mov_b32_e32 v90, v198
	v_mov_b32_e32 v91, v177
	v_lshlrev_b64 v[200:201], 1, v[90:91]
	v_lshl_add_u64 v[90:91], s[90:91], 0, v[200:201]
	v_lshl_add_u64 v[202:203], s[86:87], 0, v[200:201]
	global_load_dwordx2 v[200:201], v[90:91], off
	global_load_dwordx2 v[204:205], v[202:203], off
	v_mov_b32_e32 v203, v177
	v_or_b32_e32 v202, v176, v150
	v_mov_b32_e32 v150, v190
	v_lshlrev_b64 v[176:177], 1, v[202:203]
	v_lshl_add_u64 v[206:207], s[90:91], 0, v[176:177]
	v_lshl_add_u64 v[208:209], s[86:87], 0, v[176:177]
	global_load_dwordx2 v[176:177], v[206:207], off
	global_load_dwordx2 v[210:211], v[208:209], off
	v_mov_b32_e32 v208, v202
	v_mov_b32_e32 v202, v90
	s_waitcnt vmcnt(0)
	v_mov_b32_e32 v125, v103
	v_mov_b32_e32 v102, v96
	v_and_b32_e32 v103, 0xffff0000, v127
	v_mov_b32_e32 v96, v92
	v_and_b32_e32 v97, 0xffff0000, v129
	s_nop 0
	v_mov_b32_e32 v93, v97
	v_lshlrev_b32_e32 v92, 16, v129
	v_mov_b32_e32 v96, v128
	v_and_b32_e32 v97, 0xffff0000, v128
	s_nop 0
	v_mov_b32_e32 v129, v97
	v_lshlrev_b32_e32 v128, 16, v96
	s_nop 0
	v_mul_f32_e32 v85, 0xbfb8aa3b, v128
	s_nop 0
	v_exp_f32_e32 v96, v85
	v_mov_b32_e32 v213, v103
	v_lshlrev_b32_e32 v212, 16, v127
	v_mov_b32_e32 v102, v126
	v_and_b32_e32 v103, 0xffff0000, v126
	s_nop 0
	v_mov_b32_e32 v127, v103
	v_lshlrev_b32_e32 v126, 16, v102
	v_add_f32_e32 v85, 1.0, v96
	v_mov_b32_e32 v97, v121
	v_rcp_f32_e32 v96, v85
	v_mul_f32_e32 v85, 0xbfb8aa3b, v129
	s_nop 0
	v_exp_f32_e32 v102, v85
	s_nop 0
	v_add_f32_e32 v85, 1.0, v102
	v_mov_b32_e32 v102, v96
	v_rcp_f32_e32 v103, v85
	v_mul_f32_e32 v85, 0xbfb8aa3b, v92
	s_nop 0
	v_exp_f32_e32 v96, v85
	v_pk_mul_f32 v[120:121], v[102:103], v[128:129]
	v_mov_b32_e32 v128, v124
	v_add_f32_e32 v129, 1.0, v96
	v_mov_b32_e32 v97, v95
	v_rcp_f32_e32 v96, v129
	v_pk_add_f32 v[94:95], v[30:31], v[128:129] op_sel_hi:[1,0]
	v_pk_add_f32 v[124:125], v[28:29], v[128:129] op_sel_hi:[1,0]
	v_mul_f32_e32 v85, 0xbfb8aa3b, v93
	s_nop 0
	v_exp_f32_e32 v214, v85
	v_pk_mul_f32 v[216:217], v[124:125], v[126:127]
	v_pk_mul_f32 v[124:125], v[94:95], v[212:213]
	v_pk_mul_f32 v[94:95], v[216:217], v[120:121]
	v_add_f32_e32 v85, 1.0, v214
	v_mov_b32_e32 v120, v96
	v_rcp_f32_e32 v121, v85
	v_mov_b32_e32 v97, v95
	v_cvt_pk_bf16_f32 v96, v94, v95
	v_pk_mul_f32 v[94:95], v[120:121], v[92:93]
	s_nop 0
	v_pk_mul_f32 v[120:121], v[124:125], v[94:95]
	v_mov_b32_e32 v124, v96
	v_cvt_pk_bf16_f32 v125, v120, v121
	global_store_dwordx2 v[100:101], v[124:125], off
	v_mov_b32_e32 v123, v125
	v_mov_b32_e32 v96, v102
	v_and_b32_e32 v97, 0xffff0000, v133
	v_and_b32_e32 v135, 0xffff0000, v145
	s_nop 0
	v_mov_b32_e32 v101, v135
	v_lshlrev_b32_e32 v100, 16, v145
	v_mov_b32_e32 v102, v144
	v_and_b32_e32 v103, 0xffff0000, v144
	s_nop 0
	v_mov_b32_e32 v121, v103
	v_lshlrev_b32_e32 v120, 16, v102
	s_nop 0
	v_mul_f32_e32 v85, 0xbfb8aa3b, v120
	s_nop 0
	v_exp_f32_e32 v102, v85
	v_mov_b32_e32 v123, v97
	v_lshlrev_b32_e32 v122, 16, v133
	v_mov_b32_e32 v96, v132
	v_and_b32_e32 v97, 0xffff0000, v132
	s_nop 0
	v_mov_b32_e32 v125, v97
	v_lshlrev_b32_e32 v124, 16, v96
	v_add_f32_e32 v85, 1.0, v102
	v_mov_b32_e32 v97, v95
	v_rcp_f32_e32 v96, v85
	v_mul_f32_e32 v85, 0xbfb8aa3b, v121
	s_nop 0
	v_exp_f32_e32 v94, v85
	s_nop 0
	v_add_f32_e32 v85, 1.0, v94
	v_mov_b32_e32 v94, v96
	v_rcp_f32_e32 v95, v85
	v_mul_f32_e32 v85, 0xbfb8aa3b, v100
	s_nop 0
	v_exp_f32_e32 v96, v85
	v_pk_mul_f32 v[102:103], v[94:95], v[120:121]
	v_mov_b32_e32 v120, v128
	v_add_f32_e32 v121, 1.0, v96
	v_mov_b32_e32 v97, v93
	v_rcp_f32_e32 v96, v121
	v_pk_add_f32 v[92:93], v[26:27], v[120:121] op_sel_hi:[1,0]
	v_pk_add_f32 v[126:127], v[24:25], v[120:121] op_sel_hi:[1,0]
	v_mul_f32_e32 v85, 0xbfb8aa3b, v101
	s_nop 0
	v_exp_f32_e32 v128, v85
	v_pk_mul_f32 v[132:133], v[126:127], v[124:125]
	v_pk_mul_f32 v[124:125], v[92:93], v[122:123]
	v_pk_mul_f32 v[92:93], v[132:133], v[102:103]
	v_add_f32_e32 v85, 1.0, v128
	v_mov_b32_e32 v102, v96
	v_rcp_f32_e32 v103, v85
	v_mov_b32_e32 v97, v93
	v_cvt_pk_bf16_f32 v96, v92, v93
	v_pk_mul_f32 v[92:93], v[102:103], v[100:101]
	s_nop 0
	v_pk_mul_f32 v[102:103], v[124:125], v[92:93]
	v_mov_b32_e32 v122, v96
	v_cvt_pk_bf16_f32 v123, v102, v103
	global_store_dwordx2 v[130:131], v[122:123], off
	v_mov_b32_e32 v147, v123
	v_mov_b32_e32 v96, v94
	v_and_b32_e32 v97, 0xffff0000, v153
	v_and_b32_e32 v159, 0xffff0000, v157
	s_nop 0
	v_mov_b32_e32 v95, v159
	v_lshlrev_b32_e32 v94, 16, v157
	v_mov_b32_e32 v102, v156
	v_and_b32_e32 v103, 0xffff0000, v156
	s_nop 0
	v_mov_b32_e32 v123, v103
	v_lshlrev_b32_e32 v122, 16, v102
	s_nop 0
	v_mul_f32_e32 v85, 0xbfb8aa3b, v122
	s_nop 0
	v_exp_f32_e32 v102, v85
	v_mov_b32_e32 v125, v97
	v_lshlrev_b32_e32 v124, 16, v153
	v_mov_b32_e32 v96, v152
	v_and_b32_e32 v97, 0xffff0000, v152
	s_nop 0
	v_mov_b32_e32 v127, v97
	v_lshlrev_b32_e32 v126, 16, v96
	v_add_f32_e32 v85, 1.0, v102
	v_mov_b32_e32 v97, v93
	v_rcp_f32_e32 v96, v85
	v_mul_f32_e32 v85, 0xbfb8aa3b, v123
	s_nop 0
	v_exp_f32_e32 v92, v85
	s_nop 0
	v_add_f32_e32 v85, 1.0, v92
	v_mov_b32_e32 v92, v96
	v_rcp_f32_e32 v93, v85
	v_mul_f32_e32 v85, 0xbfb8aa3b, v94
	s_nop 0
	v_exp_f32_e32 v96, v85
	v_pk_mul_f32 v[102:103], v[92:93], v[122:123]
	v_mov_b32_e32 v92, v120
	v_add_f32_e32 v93, 1.0, v96
	s_nop 0
	v_pk_add_f32 v[96:97], v[20:21], v[92:93] op_sel_hi:[1,0]
	v_mov_b32_e32 v121, v101
	v_rcp_f32_e32 v120, v93
	v_pk_mul_f32 v[100:101], v[96:97], v[126:127]
	v_mul_f32_e32 v85, 0xbfb8aa3b, v95
	s_nop 0
	v_exp_f32_e32 v96, v85
	v_pk_add_f32 v[122:123], v[22:23], v[92:93] op_sel_hi:[1,0]
	v_pk_mul_f32 v[126:127], v[100:101], v[102:103]
	v_pk_mul_f32 v[100:101], v[122:123], v[124:125]
	v_add_f32_e32 v85, 1.0, v96
	v_mov_b32_e32 v96, v120
	v_rcp_f32_e32 v97, v85
	v_mov_b32_e32 v103, v127
	v_cvt_pk_bf16_f32 v102, v126, v127
	v_pk_add_f32 v[120:121], v[16:17], v[92:93] op_sel_hi:[1,0]
	v_pk_add_f32 v[122:123], v[18:19], v[92:93] op_sel_hi:[1,0]
	v_pk_mul_f32 v[124:125], v[96:97], v[94:95]
	s_nop 0
	v_pk_mul_f32 v[96:97], v[100:101], v[124:125]
	v_mov_b32_e32 v100, v102
	v_cvt_pk_bf16_f32 v101, v96, v97
	global_store_dwordx2 v[148:149], v[100:101], off
	v_and_b32_e32 v169, 0xffff0000, v165
	v_and_b32_e32 v155, 0xffff0000, v171
	s_nop 0
	v_mov_b32_e32 v97, v155
	v_lshlrev_b32_e32 v96, 16, v171
	v_mov_b32_e32 v100, v170
	v_and_b32_e32 v101, 0xffff0000, v170
	s_nop 0
	v_mov_b32_e32 v103, v101
	v_lshlrev_b32_e32 v102, 16, v100
	v_mov_b32_e32 v101, v169
	v_lshlrev_b32_e32 v100, 16, v165
	v_mov_b32_e32 v124, v164
	v_and_b32_e32 v125, 0xffff0000, v164
	s_nop 0
	v_mov_b32_e32 v127, v125
	v_lshlrev_b32_e32 v126, 16, v124
	v_mul_f32_e32 v85, 0xbfb8aa3b, v102
	v_mul_f32_e32 v124, 0xbfb8aa3b, v103
	v_mul_f32_e32 v125, 0xbfb8aa3b, v96
	v_pk_mul_f32 v[128:129], v[120:121], v[126:127]
	v_mul_f32_e32 v120, 0xbfb8aa3b, v97
	v_exp_f32_e32 v121, v85
	v_exp_f32_e32 v85, v124
	v_exp_f32_e32 v124, v125
	v_exp_f32_e32 v125, v120
	v_add_f32_e32 v120, 1.0, v121
	v_add_f32_e32 v121, 1.0, v85
	v_add_f32_e32 v85, 1.0, v124
	v_add_f32_e32 v124, 1.0, v125
	v_mov_b32_e32 v127, v121
	v_rcp_f32_e32 v126, v120
	s_nop 0
	v_mov_b32_e32 v120, v126
	v_rcp_f32_e32 v121, v127
	v_mov_b32_e32 v127, v95
	v_rcp_f32_e32 v126, v85
	s_nop 0
	v_mov_b32_e32 v94, v126
	v_rcp_f32_e32 v95, v124
	v_pk_mul_f32 v[124:125], v[122:123], v[100:101]
	v_pk_mul_f32 v[100:101], v[120:121], v[102:103]
	v_pk_mul_f32 v[102:103], v[94:95], v[96:97]
	s_nop 0
	v_pk_mul_f32 v[122:123], v[124:125], v[102:103]
	v_pk_mul_f32 v[102:103], v[128:129], v[100:101]
	s_nop 0
	v_mov_b32_e32 v125, v103
	v_cvt_pk_bf16_f32 v124, v102, v103
	s_nop 0
	v_mov_b32_e32 v102, v124
	v_cvt_pk_bf16_f32 v103, v122, v123
	v_mov_b32_e32 v173, v123
	v_mov_b32_e32 v175, v101
	global_store_dwordx2 v[166:167], v[102:103], off
	v_mov_b32_e32 v185, v103
	v_mov_b32_e32 v100, v92
	v_and_b32_e32 v101, 0xffff0000, v99
	v_mov_b32_e32 v92, v96
	v_and_b32_e32 v93, 0xffff0000, v189
	s_nop 0
	v_mov_b32_e32 v97, v93
	v_lshlrev_b32_e32 v96, 16, v189
	v_mov_b32_e32 v92, v188
	v_and_b32_e32 v93, 0xffff0000, v188
	s_nop 0
	v_mov_b32_e32 v103, v93
	v_lshlrev_b32_e32 v102, 16, v92
	s_nop 0
	v_mul_f32_e32 v85, 0xbfb8aa3b, v102
	s_nop 0
	v_exp_f32_e32 v92, v85
	v_mov_b32_e32 v123, v101
	v_lshlrev_b32_e32 v122, 16, v99
	v_mov_b32_e32 v100, v98
	v_and_b32_e32 v101, 0xffff0000, v98
	s_nop 0
	v_mov_b32_e32 v99, v101
	v_lshlrev_b32_e32 v98, 16, v100
	v_add_f32_e32 v85, 1.0, v92
	v_mov_b32_e32 v93, v121
	v_rcp_f32_e32 v92, v85
	v_mul_f32_e32 v85, 0xbfb8aa3b, v103
	s_nop 0
	v_exp_f32_e32 v100, v85
	s_nop 0
	v_add_f32_e32 v85, 1.0, v100
	v_mov_b32_e32 v100, v92
	v_rcp_f32_e32 v101, v85
	v_mul_f32_e32 v85, 0xbfb8aa3b, v96
	s_nop 0
	v_exp_f32_e32 v92, v85
	v_pk_mul_f32 v[120:121], v[100:101], v[102:103]
	v_mov_b32_e32 v102, v184
	v_add_f32_e32 v103, 1.0, v92
	v_mov_b32_e32 v93, v95
	v_rcp_f32_e32 v92, v103
	v_pk_add_f32 v[94:95], v[14:15], v[102:103] op_sel_hi:[1,0]
	v_pk_add_f32 v[124:125], v[12:13], v[102:103] op_sel_hi:[1,0]
	v_mul_f32_e32 v85, 0xbfb8aa3b, v97
	s_nop 0
	v_exp_f32_e32 v126, v85
	v_pk_mul_f32 v[128:129], v[124:125], v[98:99]
	v_pk_mul_f32 v[98:99], v[94:95], v[122:123]
	v_pk_mul_f32 v[94:95], v[128:129], v[120:121]
	v_add_f32_e32 v85, 1.0, v126
	v_mov_b32_e32 v120, v92
	v_rcp_f32_e32 v121, v85
	v_mov_b32_e32 v93, v95
	v_cvt_pk_bf16_f32 v92, v94, v95
	v_pk_mul_f32 v[94:95], v[120:121], v[96:97]
	s_nop 0
	v_pk_mul_f32 v[120:121], v[98:99], v[94:95]
	v_mov_b32_e32 v98, v92
	v_cvt_pk_bf16_f32 v99, v120, v121
	global_store_dwordx2 v[178:179], v[98:99], off
	v_mov_b32_e32 v187, v99
	v_mov_b32_e32 v92, v100
	v_and_b32_e32 v93, 0xffff0000, v193
	v_and_b32_e32 v195, 0xffff0000, v197
	s_nop 0
	v_mov_b32_e32 v99, v195
	v_lshlrev_b32_e32 v98, 16, v197
	v_mov_b32_e32 v100, v196
	v_and_b32_e32 v101, 0xffff0000, v196
	s_nop 0
	v_mov_b32_e32 v121, v101
	v_lshlrev_b32_e32 v120, 16, v100
	s_nop 0
	v_mul_f32_e32 v85, 0xbfb8aa3b, v120
	s_nop 0
	v_exp_f32_e32 v100, v85
	v_mov_b32_e32 v123, v93
	v_lshlrev_b32_e32 v122, 16, v193
	v_mov_b32_e32 v92, v192
	v_and_b32_e32 v93, 0xffff0000, v192
	s_nop 0
	v_mov_b32_e32 v125, v93
	v_lshlrev_b32_e32 v124, 16, v92
	v_add_f32_e32 v85, 1.0, v100
	v_mov_b32_e32 v93, v95
	v_rcp_f32_e32 v92, v85
	v_mul_f32_e32 v85, 0xbfb8aa3b, v121
	s_nop 0
	v_exp_f32_e32 v94, v85
	s_nop 0
	v_add_f32_e32 v85, 1.0, v94
	v_mov_b32_e32 v94, v92
	v_rcp_f32_e32 v95, v85
	v_mul_f32_e32 v85, 0xbfb8aa3b, v98
	s_nop 0
	v_exp_f32_e32 v92, v85
	v_pk_mul_f32 v[100:101], v[94:95], v[120:121]
	v_mov_b32_e32 v120, v102
	v_add_f32_e32 v121, 1.0, v92
	v_mov_b32_e32 v93, v97
	v_rcp_f32_e32 v92, v121
	v_pk_add_f32 v[96:97], v[10:11], v[120:121] op_sel_hi:[1,0]
	v_pk_add_f32 v[102:103], v[8:9], v[120:121] op_sel_hi:[1,0]
	v_mul_f32_e32 v85, 0xbfb8aa3b, v99
	s_nop 0
	v_exp_f32_e32 v126, v85
	v_pk_mul_f32 v[128:129], v[102:103], v[124:125]
	v_pk_mul_f32 v[102:103], v[96:97], v[122:123]
	v_pk_mul_f32 v[96:97], v[128:129], v[100:101]
	v_add_f32_e32 v85, 1.0, v126
	v_mov_b32_e32 v100, v92
	v_rcp_f32_e32 v101, v85
	v_mov_b32_e32 v93, v97
	v_cvt_pk_bf16_f32 v92, v96, v97
	v_pk_mul_f32 v[96:97], v[100:101], v[98:99]
	s_nop 0
	v_pk_mul_f32 v[100:101], v[102:103], v[96:97]
	v_mov_b32_e32 v102, v92
	v_cvt_pk_bf16_f32 v103, v100, v101
	global_store_dwordx2 v[190:191], v[102:103], off
	v_mov_b32_e32 v199, v103
	v_mov_b32_e32 v92, v94
	v_and_b32_e32 v93, 0xffff0000, v201
	v_and_b32_e32 v151, 0xffff0000, v205
	s_nop 0
	v_mov_b32_e32 v95, v151
	v_lshlrev_b32_e32 v94, 16, v205
	v_mov_b32_e32 v100, v204
	v_and_b32_e32 v101, 0xffff0000, v204
	s_nop 0
	v_mov_b32_e32 v103, v101
	v_lshlrev_b32_e32 v102, 16, v100
	s_nop 0
	v_mul_f32_e32 v85, 0xbfb8aa3b, v102
	s_nop 0
	v_exp_f32_e32 v100, v85
	v_mov_b32_e32 v123, v93
	v_lshlrev_b32_e32 v122, 16, v201
	v_mov_b32_e32 v92, v200
	v_and_b32_e32 v93, 0xffff0000, v200
	s_nop 0
	v_mov_b32_e32 v125, v93
	v_lshlrev_b32_e32 v124, 16, v92
	v_add_f32_e32 v85, 1.0, v100
	v_mov_b32_e32 v93, v97
	v_rcp_f32_e32 v92, v85
	v_mul_f32_e32 v85, 0xbfb8aa3b, v103
	s_nop 0
	v_exp_f32_e32 v96, v85
	s_nop 0
	v_add_f32_e32 v85, 1.0, v96
	v_mov_b32_e32 v96, v92
	v_rcp_f32_e32 v97, v85
	v_mul_f32_e32 v85, 0xbfb8aa3b, v94
	s_nop 0
	v_exp_f32_e32 v92, v85
	v_pk_mul_f32 v[100:101], v[96:97], v[102:103]
	v_mov_b32_e32 v96, v120
	v_add_f32_e32 v97, 1.0, v92
	s_nop 0
	v_pk_add_f32 v[92:93], v[4:5], v[96:97] op_sel_hi:[1,0]
	v_mov_b32_e32 v103, v99
	v_rcp_f32_e32 v102, v97
	v_pk_mul_f32 v[98:99], v[92:93], v[124:125]
	v_mul_f32_e32 v85, 0xbfb8aa3b, v95
	s_nop 0
	v_exp_f32_e32 v92, v85
	v_pk_add_f32 v[120:121], v[6:7], v[96:97] op_sel_hi:[1,0]
	v_pk_mul_f32 v[124:125], v[98:99], v[100:101]
	v_pk_mul_f32 v[98:99], v[120:121], v[122:123]
	v_add_f32_e32 v85, 1.0, v92
	v_mov_b32_e32 v92, v102
	v_rcp_f32_e32 v93, v85
	v_mov_b32_e32 v101, v125
	v_cvt_pk_bf16_f32 v100, v124, v125
	v_pk_add_f32 v[102:103], v[0:1], v[96:97] op_sel_hi:[1,0]
	v_pk_add_f32 v[120:121], v[2:3], v[96:97] op_sel_hi:[1,0]
	v_pk_mul_f32 v[96:97], v[92:93], v[94:95]
	s_nop 0
	v_pk_mul_f32 v[92:93], v[98:99], v[96:97]
	v_mov_b32_e32 v96, v100
	v_cvt_pk_bf16_f32 v97, v92, v93
	global_store_dwordx2 v[90:91], v[96:97], off
	v_and_b32_e32 v209, 0xffff0000, v177
	v_and_b32_e32 v203, 0xffff0000, v211
	s_nop 0
	v_mov_b32_e32 v91, v203
	v_lshlrev_b32_e32 v90, 16, v211
	v_mov_b32_e32 v92, v210
	v_and_b32_e32 v93, 0xffff0000, v210
	s_nop 0
	v_mov_b32_e32 v97, v93
	v_lshlrev_b32_e32 v96, 16, v92
	v_mov_b32_e32 v93, v209
	v_lshlrev_b32_e32 v92, 16, v177
	v_mov_b32_e32 v98, v176
	v_and_b32_e32 v99, 0xffff0000, v176
	s_nop 0
	v_mov_b32_e32 v101, v99
	v_lshlrev_b32_e32 v100, 16, v98
	v_mul_f32_e32 v85, 0xbfb8aa3b, v96
	v_mul_f32_e32 v98, 0xbfb8aa3b, v97
	v_mul_f32_e32 v99, 0xbfb8aa3b, v90
	v_pk_mul_f32 v[122:123], v[102:103], v[100:101]
	v_mul_f32_e32 v100, 0xbfb8aa3b, v91
	v_exp_f32_e32 v101, v85
	v_exp_f32_e32 v85, v98
	v_exp_f32_e32 v98, v99
	v_exp_f32_e32 v99, v100
	v_add_f32_e32 v100, 1.0, v101
	v_add_f32_e32 v101, 1.0, v85
	v_add_f32_e32 v85, 1.0, v98
	v_add_f32_e32 v98, 1.0, v99
	v_mov_b32_e32 v103, v101
	v_rcp_f32_e32 v102, v100
	s_nop 0
	v_mov_b32_e32 v100, v102
	v_rcp_f32_e32 v101, v103
	v_mov_b32_e32 v103, v95
	v_rcp_f32_e32 v102, v85
	s_nop 0
	v_mov_b32_e32 v94, v102
	v_rcp_f32_e32 v95, v98
	v_pk_mul_f32 v[98:99], v[120:121], v[92:93]
	v_pk_mul_f32 v[92:93], v[100:101], v[96:97]
	v_pk_mul_f32 v[96:97], v[94:95], v[90:91]
	s_nop 0
	v_pk_mul_f32 v[90:91], v[98:99], v[96:97]
	v_pk_mul_f32 v[94:95], v[122:123], v[92:93]
	s_nop 0
	v_mov_b32_e32 v93, v95
	v_cvt_pk_bf16_f32 v92, v94, v95
	s_nop 0
	v_mov_b32_e32 v94, v92
	v_cvt_pk_bf16_f32 v95, v90, v91
	global_store_dwordx2 v[206:207], v[94:95], off
	s_cbranch_scc1 .LBB0_1654
